# NSA selected-branch steps: tile index kept in its SGPR instead of re-read from LDS after QK (one exposed LDS round trip less per step)
# speedup vs baseline: 1.0071x; 1.0043x over previous
; template <int MODE, int SLOT> DI void ns_valu(volatile LAS int* jl, int t, int ntl, int qpos, int h, int blk, f32x16& s0, f32x16& s1, f32x16& du0, f32x16& du1, f32x16 (&O)[2], float& muse, float& l, bf16x8 (&P)[4], CmpCap& cap) {
;     if (t < ntl) {
;       const int j = __builtin_amdgcn_readfirstlane(jl[t]);
;       if (MODE == 0) {
;         const int lim = ((qpos - 31) >> 4) - 64 * j - 4 * h;
; #pragma unroll
;         for (int i = 0; i < 16; ++i) { const int ci = (i & 3) + 8 * (i >> 2); if (ci > lim) s0[i] = NEG; if (ci + 32 > lim) s1[i] = NEG; }
;       } else if (MODE == 1) {
;         if (j == blk) {
;           const int lim = qpos - 64 * j - 4 * h;
; #pragma unroll
;           for (int i = 0; i < 16; ++i) { const int ci = (i & 3) + 8 * (i >> 2); if (ci > lim) s0[i] = NEG; if (ci + 32 > lim) s1[i] = NEG; }
;         }
.LBB0_940:
	s_mul_i32 s94, s6, 0x4800
	s_add_i32 s95, s94, 0
	v_mov_b32_e32 v139, s90
	v_add_u32_e32 v33, s95, v213
	ds_read_b32 v32, v139
	ds_read_b128 v[96:99], v33 offset:4608
	ds_read_b128 v[100:103], v33
	ds_read_b128 v[104:107], v33 offset:32
	ds_read_b128 v[108:111], v33 offset:4640
	ds_read_b128 v[112:115], v33 offset:64
	ds_read_b128 v[116:119], v33 offset:4672
	ds_read_b128 v[120:123], v33 offset:96
	ds_read_b128 v[124:127], v33 offset:4704
	s_waitcnt lgkmcnt(8)
	v_readfirstlane_b32 s84, v32
	s_nop 1
	v_lshrrev_b32_e32 v32, s84, v137
	v_and_b32_e32 v32, 1, v32
	v_cmp_eq_u32_e32 vcc, 1, v32
	s_nop 1
	v_cndmask_b32_e64 v32, v207, -v138, vcc
	v_mov_b32_e32 v33, v32
	v_mov_b32_e32 v34, v32
	v_mov_b32_e32 v35, v32
	v_mov_b32_e32 v36, v32
	v_mov_b32_e32 v37, v32
	v_mov_b32_e32 v38, v32
	v_mov_b32_e32 v39, v32
	v_mov_b32_e32 v40, v32
	v_mov_b32_e32 v41, v32
	v_mov_b32_e32 v42, v32
	v_mov_b32_e32 v43, v32
	v_mov_b32_e32 v44, v32
	v_mov_b32_e32 v45, v32
	v_mov_b32_e32 v46, v32
	v_mov_b32_e32 v47, v32
	s_setprio 1
	s_waitcnt lgkmcnt(6)
	v_mfma_f32_32x32x16_bf16 v[48:63], v[100:103], v[160:163], v[32:47]
	v_mfma_f32_32x32x16_bf16 v[32:47], v[96:99], v[160:163], v[32:47]
	s_waitcnt lgkmcnt(5)
	v_mfma_f32_32x32x16_bf16 v[48:63], v[104:107], v[168:171], v[48:63]
	s_waitcnt lgkmcnt(4)
	v_mfma_f32_32x32x16_bf16 v[32:47], v[108:111], v[168:171], v[32:47]
	s_waitcnt lgkmcnt(3)
	v_mfma_f32_32x32x16_bf16 v[48:63], v[112:115], v[164:167], v[48:63]
	s_waitcnt lgkmcnt(2)
	v_mfma_f32_32x32x16_bf16 v[32:47], v[116:119], v[164:167], v[32:47]
	s_waitcnt lgkmcnt(1)
	v_mfma_f32_32x32x16_bf16 v[48:63], v[120:123], v[172:175], v[48:63]
	s_waitcnt lgkmcnt(0)
	v_mfma_f32_32x32x16_bf16 v[32:47], v[124:127], v[172:175], v[32:47]
	s_setprio 0
	s_cmp_lg_u32 s84, s77
	s_cbranch_scc1 .LBB0_944
	s_and_b64 vcc, s[70:71], s[66:67]
	s_nop 7
	v_cndmask_b32_e32 v45, v45, v207, vcc
	s_and_b64 vcc, vcc, s[62:63]
	v_cndmask_b32_e32 v44, v44, v207, vcc
	s_and_b64 vcc, vcc, s[58:59]
	v_cndmask_b32_e32 v43, v43, v207, vcc
	s_and_b64 vcc, vcc, s[54:55]
	v_cndmask_b32_e32 v42, v42, v207, vcc
	s_and_b64 vcc, vcc, s[50:51]
	v_cndmask_b32_e32 v41, v41, v207, vcc
	s_and_b64 vcc, vcc, s[46:47]
	v_cndmask_b32_e32 v40, v40, v207, vcc
	s_and_b64 vcc, vcc, s[42:43]
	v_cndmask_b32_e32 v39, v39, v207, vcc
	s_and_b64 vcc, vcc, s[38:39]
	v_cndmask_b32_e32 v38, v38, v207, vcc
	s_and_b64 vcc, vcc, s[34:35]
	v_cndmask_b32_e32 v37, v37, v207, vcc
	s_and_b64 vcc, vcc, s[28:29]
	v_cndmask_b32_e32 v36, v36, v207, vcc
	s_and_b64 vcc, vcc, s[24:25]
	v_cndmask_b32_e32 v35, v35, v207, vcc
	s_and_b64 vcc, vcc, s[20:21]
	v_cndmask_b32_e32 v34, v34, v207, vcc
	s_and_b64 vcc, vcc, s[16:17]
	v_cndmask_b32_e32 v33, v33, v207, vcc
	s_and_b64 vcc, vcc, s[12:13]
	v_cndmask_b32_e64 v46, v46, v207, s[70:71]
	v_cndmask_b32_e32 v32, v32, v207, vcc
	s_and_saveexec_b64 s[84:85], s[74:75]
	s_mov_b32 s86, 0xf149f2ca
	v_mov_b32_e32 v47, s86
	s_or_b64 exec, exec, s[84:85]
	s_and_b64 vcc, s[72:73], s[68:69]
	v_cndmask_b32_e32 v62, v62, v207, vcc
	s_and_b64 vcc, vcc, s[64:65]
	v_cndmask_b32_e32 v61, v61, v207, vcc
	s_and_b64 vcc, vcc, s[60:61]
	v_cndmask_b32_e32 v60, v60, v207, vcc
	s_and_b64 vcc, vcc, s[56:57]
	v_cndmask_b32_e32 v59, v59, v207, vcc
	s_and_b64 vcc, vcc, s[52:53]
	v_cndmask_b32_e32 v58, v58, v207, vcc
	s_and_b64 vcc, vcc, s[48:49]
	v_cndmask_b32_e32 v57, v57, v207, vcc
	s_and_b64 vcc, vcc, s[44:45]
	v_cndmask_b32_e32 v56, v56, v207, vcc
	s_and_b64 vcc, vcc, s[40:41]
	v_cndmask_b32_e32 v55, v55, v207, vcc
	s_and_b64 vcc, vcc, s[36:37]
	v_cndmask_b32_e32 v54, v54, v207, vcc
	s_and_b64 vcc, vcc, s[30:31]
	v_cndmask_b32_e32 v53, v53, v207, vcc
	s_and_b64 vcc, vcc, s[26:27]
	v_cndmask_b32_e32 v52, v52, v207, vcc
	s_and_b64 vcc, vcc, s[22:23]
	v_cndmask_b32_e32 v51, v51, v207, vcc
	s_and_b64 vcc, vcc, s[18:19]
	v_cndmask_b32_e32 v50, v50, v207, vcc
	s_and_b64 vcc, vcc, s[14:15]
	v_cndmask_b32_e32 v49, v49, v207, vcc
	s_and_b64 vcc, vcc, s[10:11]
	v_cndmask_b32_e64 v63, v63, v207, s[72:73]
	v_cndmask_b32_e32 v48, v48, v207, vcc
.LBB0_944:
	s_nop 6
	v_max_f32_e32 v96, v49, v49
	v_max_f32_e32 v97, v48, v48
	v_max_f32_e32 v96, v97, v96
	v_max3_f32 v97, v50, v51, v33
	v_max3_f32 v96, v96, v32, v34
	v_max3_f32 v96, v96, v35, v52
	v_max3_f32 v97, v97, v54, v55
	v_max3_f32 v96, v96, v53, v36
	v_max3_f32 v97, v97, v38, v39
	v_max3_f32 v96, v96, v37, v56
	v_max3_f32 v97, v97, v58, v59
	v_max3_f32 v96, v96, v57, v40
	v_max3_f32 v97, v97, v42, v43
	v_max3_f32 v96, v96, v41, v60
	v_max3_f32 v97, v97, v62, v63
	v_max3_f32 v96, v96, v61, v44
	v_max3_f32 v97, v97, v46, v47
	v_max3_f32 v96, v96, v45, v97
	ds_bpermute_b32 v97, v193, v96
	s_cmp_lg_u32 s89, 3
	s_waitcnt lgkmcnt(0)
	v_max_f32_e32 v97, v97, v97
	v_max_f32_e32 v96, v96, v97
	s_cbranch_scc0 .LBB0_962
	v_cmp_lt_f32_e32 vcc, s7, v96
	s_mov_b64 s[86:87], 0
	s_mov_b64 s[84:85], 0
	s_cbranch_vccz .LBB0_947
	v_max_f32_e32 v97, v96, v96
	v_max_f32_e32 v97, 0, v97
	s_mov_b64 s[84:85], -1

; template <int MODE, int SLOT> DI void ns_valu(volatile LAS int* jl, int t, int ntl, int qpos, int h, int blk, f32x16& s0, f32x16& s1, f32x16& du0, f32x16& du1, f32x16 (&O)[2], float& muse, float& l, bf16x8 (&P)[4], CmpCap& cap) {
;     if (t < ntl) {
;       const int j = __builtin_amdgcn_readfirstlane(jl[t]);
;       if (MODE == 0) {
;         const int lim = ((qpos - 31) >> 4) - 64 * j - 4 * h;
; #pragma unroll
;         for (int i = 0; i < 16; ++i) { const int ci = (i & 3) + 8 * (i >> 2); if (ci > lim) s0[i] = NEG; if (ci + 32 > lim) s1[i] = NEG; }
;       } else if (MODE == 1) {
;         if (j == blk) {
;           const int lim = qpos - 64 * j - 4 * h;
; #pragma unroll
;           for (int i = 0; i < 16; ++i) { const int ci = (i & 3) + 8 * (i >> 2); if (ci > lim) s0[i] = NEG; if (ci + 32 > lim) s1[i] = NEG; }
;         }
.LBB0_956:
	s_add_i32 s84, s6, 1
	s_cmp_lg_u32 s6, 2
	s_cselect_b32 s6, s84, 0
	v_mov_b32_e32 v140, s90
	ds_read_b32 v32, v140 offset:4
	s_mul_i32 s86, s6, 0x4800
	s_add_i32 s87, s86, 0
	v_add_u32_e32 v60, s87, v213
	s_waitcnt lgkmcnt(0)
	v_readfirstlane_b32 s84, v32
	s_nop 1
	v_lshrrev_b32_e32 v32, s84, v137
	v_and_b32_e32 v32, 1, v32
	v_cmp_eq_u32_e32 vcc, 1, v32
	ds_read_b128 v[32:35], v60 offset:4608
	ds_read_b128 v[36:39], v60
	ds_read_b128 v[40:43], v60 offset:32
	ds_read_b128 v[44:47], v60 offset:4640
	ds_read_b128 v[48:51], v60 offset:64
	ds_read_b128 v[52:55], v60 offset:4672
	ds_read_b128 v[56:59], v60 offset:96
	ds_read_b128 v[60:63], v60 offset:4704
	v_cndmask_b32_e64 v96, v207, -v138, vcc
	v_mov_b32_e32 v97, v96
	v_mov_b32_e32 v98, v96
	v_mov_b32_e32 v99, v96
	v_mov_b32_e32 v100, v96
	v_mov_b32_e32 v101, v96
	v_mov_b32_e32 v102, v96
	v_mov_b32_e32 v103, v96
	v_mov_b32_e32 v104, v96
	v_mov_b32_e32 v105, v96
	v_mov_b32_e32 v106, v96
	v_mov_b32_e32 v107, v96
	v_mov_b32_e32 v108, v96
	v_mov_b32_e32 v109, v96
	v_mov_b32_e32 v110, v96
	v_mov_b32_e32 v111, v96
	s_setprio 1
	s_waitcnt lgkmcnt(6)
	v_mfma_f32_32x32x16_bf16 v[112:127], v[36:39], v[160:163], v[96:111]
	v_mfma_f32_32x32x16_bf16 v[96:111], v[32:35], v[160:163], v[96:111]
	s_waitcnt lgkmcnt(5)
	v_mfma_f32_32x32x16_bf16 v[112:127], v[40:43], v[168:171], v[112:127]
	s_waitcnt lgkmcnt(4)
	v_mfma_f32_32x32x16_bf16 v[96:111], v[44:47], v[168:171], v[96:111]
	s_waitcnt lgkmcnt(3)
	v_mfma_f32_32x32x16_bf16 v[112:127], v[48:51], v[164:167], v[112:127]
	s_waitcnt lgkmcnt(2)
	v_mfma_f32_32x32x16_bf16 v[96:111], v[52:55], v[164:167], v[96:111]
	s_waitcnt lgkmcnt(1)
	v_mfma_f32_32x32x16_bf16 v[112:127], v[56:59], v[172:175], v[112:127]
	s_waitcnt lgkmcnt(0)
	v_mfma_f32_32x32x16_bf16 v[96:111], v[60:63], v[172:175], v[96:111]
	s_setprio 0
	s_cmp_lg_u32 s84, s77
	s_cbranch_scc1 .LBB0_960
	s_and_b64 vcc, s[70:71], s[66:67]
	s_nop 7
	v_cndmask_b32_e32 v109, v109, v207, vcc
	s_and_b64 vcc, vcc, s[62:63]
	v_cndmask_b32_e32 v108, v108, v207, vcc
	s_and_b64 vcc, vcc, s[58:59]
	v_cndmask_b32_e32 v107, v107, v207, vcc
	s_and_b64 vcc, vcc, s[54:55]
	v_cndmask_b32_e32 v106, v106, v207, vcc
	s_and_b64 vcc, vcc, s[50:51]
	v_cndmask_b32_e32 v105, v105, v207, vcc
	s_and_b64 vcc, vcc, s[46:47]
	v_cndmask_b32_e32 v104, v104, v207, vcc
	s_and_b64 vcc, vcc, s[42:43]
	v_cndmask_b32_e32 v103, v103, v207, vcc
	s_and_b64 vcc, vcc, s[38:39]
	v_cndmask_b32_e32 v102, v102, v207, vcc
	s_and_b64 vcc, vcc, s[34:35]
	v_cndmask_b32_e32 v101, v101, v207, vcc
	s_and_b64 vcc, vcc, s[28:29]
	v_cndmask_b32_e32 v100, v100, v207, vcc
	s_and_b64 vcc, vcc, s[24:25]
	v_cndmask_b32_e32 v99, v99, v207, vcc
	s_and_b64 vcc, vcc, s[20:21]
	v_cndmask_b32_e32 v98, v98, v207, vcc
	s_and_b64 vcc, vcc, s[16:17]
	v_cndmask_b32_e32 v97, v97, v207, vcc
	s_and_b64 vcc, vcc, s[12:13]
	v_cndmask_b32_e64 v110, v110, v207, s[70:71]
	v_cndmask_b32_e32 v96, v96, v207, vcc
	s_and_saveexec_b64 s[84:85], s[74:75]
	s_mov_b32 s94, 0xf149f2ca
	v_mov_b32_e32 v111, s94
	s_or_b64 exec, exec, s[84:85]
	s_and_b64 vcc, s[72:73], s[68:69]
	v_cndmask_b32_e32 v126, v126, v207, vcc
	s_and_b64 vcc, vcc, s[64:65]
	v_cndmask_b32_e32 v125, v125, v207, vcc
	s_and_b64 vcc, vcc, s[60:61]
	v_cndmask_b32_e32 v124, v124, v207, vcc
	s_and_b64 vcc, vcc, s[56:57]
	v_cndmask_b32_e32 v123, v123, v207, vcc
	s_and_b64 vcc, vcc, s[52:53]
	v_cndmask_b32_e32 v122, v122, v207, vcc
	s_and_b64 vcc, vcc, s[48:49]
	v_cndmask_b32_e32 v121, v121, v207, vcc
	s_and_b64 vcc, vcc, s[44:45]
	v_cndmask_b32_e32 v120, v120, v207, vcc
	s_and_b64 vcc, vcc, s[40:41]
	v_cndmask_b32_e32 v119, v119, v207, vcc
	s_and_b64 vcc, vcc, s[36:37]
	v_cndmask_b32_e32 v118, v118, v207, vcc
	s_and_b64 vcc, vcc, s[30:31]
	v_cndmask_b32_e32 v117, v117, v207, vcc
	s_and_b64 vcc, vcc, s[26:27]
	v_cndmask_b32_e32 v116, v116, v207, vcc
	s_and_b64 vcc, vcc, s[22:23]
	v_cndmask_b32_e32 v115, v115, v207, vcc
	s_and_b64 vcc, vcc, s[18:19]
	v_cndmask_b32_e32 v114, v114, v207, vcc
	s_and_b64 vcc, vcc, s[14:15]
	v_cndmask_b32_e32 v113, v113, v207, vcc
	s_and_b64 vcc, vcc, s[10:11]
	v_cndmask_b32_e64 v127, v127, v207, s[72:73]
	v_cndmask_b32_e32 v112, v112, v207, vcc
; DI float rowmax32(const f32x16& s0, const f32x16& s1) {
;   float a = fmaxf(fmaxf(s0[0], s0[1]), s1[0]), b = fmaxf(fmaxf(s0[2], s0[3]), s1[1]); a = fmaxf(fmaxf(a, s1[2]), s1[3]);
; #pragma unroll
;   for (int r = 4; r < 16; r += 4) { a = fmaxf(fmaxf(a, s0[r]), s0[r + 1]); b = fmaxf(fmaxf(b, s0[r + 2]), s0[r + 3]); a = fmaxf(fmaxf(a, s1[r]), s1[r + 1]); b = fmaxf(fmaxf(b, s1[r + 2]), s1[r + 3]); }
;   const float m = fmaxf(a, b);
;   return fmaxf(m, __shfl_xor(m, 32));
; }
; template <int NDVB, bool HAS_NEXT> DI void softmax_def(f32x16& sa0, f32x16& sa1, f32x16& sb0, f32x16& sb1, f32x16 (&O)[NDVB], float& muse, float& l, bool first, bf16x8 (&P)[4], bool check = true) {
;   float mx = 0.f;
;   if (check) mx = rowmax32(sa0, sa1);
;   if (check && (first || __any(mx > 8.f))) {
;     float dl = first ? mx : fmaxf(mx, 0.f);
;     if (mx < -1e29f) dl = 0.f;
;     const float alpha = __builtin_amdgcn_exp2f(-dl);
;     muse += dl; l *= alpha;
; #pragma unroll
;     for (int i = 0; i < 16; ++i) { sa0[i] -= dl; sa1[i] -= dl; }
;     if (HAS_NEXT) {
; #pragma unroll
;       for (int i = 0; i < 16; ++i) { sb0[i] -= dl; sb1[i] -= dl; }
;     }
; #pragma unroll
;     for (int d = 0; d < NDVB; ++d)
; #pragma unroll
;       for (int i = 0; i < 16; ++i) O[d][i] *= alpha;
;   }
.LBB0_960:
	s_nop 6
	v_max_f32_e32 v32, v113, v113
	v_max_f32_e32 v33, v112, v112
	v_max_f32_e32 v32, v33, v32
	v_max3_f32 v33, v114, v115, v97
	v_max3_f32 v32, v32, v96, v98
	v_max3_f32 v32, v32, v99, v116
	v_max3_f32 v33, v33, v118, v119
	v_max3_f32 v32, v32, v117, v100
	v_max3_f32 v33, v33, v102, v103
	v_max3_f32 v32, v32, v101, v120
	v_max3_f32 v33, v33, v122, v123
	v_max3_f32 v32, v32, v121, v104
	v_max3_f32 v33, v33, v106, v107
	v_max3_f32 v32, v32, v105, v124
	v_max3_f32 v33, v33, v126, v127
	v_max3_f32 v32, v32, v125, v108
	v_max3_f32 v33, v33, v110, v111
	v_max3_f32 v32, v32, v109, v33
	ds_bpermute_b32 v33, v193, v32
	s_waitcnt lgkmcnt(0)
	v_max_f32_e32 v33, v33, v33
	v_max_f32_e32 v32, v32, v33
	v_cmp_lt_f32_e32 vcc, s7, v32
	s_cbranch_vccz .LBB0_963
	v_max_f32_e32 v33, v32, v32
	v_max_f32_e32 v33, 0, v33
	v_cmp_ngt_f32_e32 vcc, s1, v32
	s_nop 1
	v_cndmask_b32_e32 v32, 0, v33, vcc
	v_exp_f32_e64 v142, -v32
	v_add_f32_e32 v138, v138, v32
	v_pk_add_f32 v[112:113], v[112:113], v[32:33] op_sel_hi:[1,0] neg_lo:[0,1] neg_hi:[0,1]
	v_pk_add_f32 v[96:97], v[96:97], v[32:33] op_sel_hi:[1,0] neg_lo:[0,1] neg_hi:[0,1]
	v_mul_f32_e32 v140, v139, v142
	v_pk_add_f32 v[114:115], v[114:115], v[32:33] op_sel_hi:[1,0] neg_lo:[0,1] neg_hi:[0,1]
	v_pk_add_f32 v[98:99], v[98:99], v[32:33] op_sel_hi:[1,0] neg_lo:[0,1] neg_hi:[0,1]
	v_pk_add_f32 v[116:117], v[116:117], v[32:33] op_sel_hi:[1,0] neg_lo:[0,1] neg_hi:[0,1]
	v_pk_add_f32 v[100:101], v[100:101], v[32:33] op_sel_hi:[1,0] neg_lo:[0,1] neg_hi:[0,1]
	v_pk_add_f32 v[118:119], v[118:119], v[32:33] op_sel_hi:[1,0] neg_lo:[0,1] neg_hi:[0,1]
	v_pk_add_f32 v[102:103], v[102:103], v[32:33] op_sel_hi:[1,0] neg_lo:[0,1] neg_hi:[0,1]
	v_pk_add_f32 v[120:121], v[120:121], v[32:33] op_sel_hi:[1,0] neg_lo:[0,1] neg_hi:[0,1]
	v_pk_add_f32 v[104:105], v[104:105], v[32:33] op_sel_hi:[1,0] neg_lo:[0,1] neg_hi:[0,1]
	v_pk_add_f32 v[122:123], v[122:123], v[32:33] op_sel_hi:[1,0] neg_lo:[0,1] neg_hi:[0,1]
	v_pk_add_f32 v[106:107], v[106:107], v[32:33] op_sel_hi:[1,0] neg_lo:[0,1] neg_hi:[0,1]
	v_pk_add_f32 v[124:125], v[124:125], v[32:33] op_sel_hi:[1,0] neg_lo:[0,1] neg_hi:[0,1]
	v_pk_add_f32 v[108:109], v[108:109], v[32:33] op_sel_hi:[1,0] neg_lo:[0,1] neg_hi:[0,1]
	v_pk_add_f32 v[126:127], v[126:127], v[32:33] op_sel_hi:[1,0] neg_lo:[0,1] neg_hi:[0,1]
	v_pk_add_f32 v[110:111], v[110:111], v[32:33] op_sel_hi:[1,0] neg_lo:[0,1] neg_hi:[0,1]
	v_pk_mul_f32 v[30:31], v[30:31], v[142:143] op_sel_hi:[1,0]
	v_pk_mul_f32 v[28:29], v[28:29], v[142:143] op_sel_hi:[1,0]
	v_pk_mul_f32 v[26:27], v[26:27], v[142:143] op_sel_hi:[1,0]
	v_pk_mul_f32 v[24:25], v[24:25], v[142:143] op_sel_hi:[1,0]
	v_pk_mul_f32 v[22:23], v[22:23], v[142:143] op_sel_hi:[1,0]
	v_pk_mul_f32 v[20:21], v[20:21], v[142:143] op_sel_hi:[1,0]
	v_pk_mul_f32 v[18:19], v[18:19], v[142:143] op_sel_hi:[1,0]
	v_pk_mul_f32 v[16:17], v[16:17], v[142:143] op_sel_hi:[1,0]
	v_pk_mul_f32 v[14:15], v[14:15], v[142:143] op_sel_hi:[1,0]
	v_pk_mul_f32 v[12:13], v[12:13], v[142:143] op_sel_hi:[1,0]
	v_pk_mul_f32 v[10:11], v[10:11], v[142:143] op_sel_hi:[1,0]
	v_pk_mul_f32 v[8:9], v[8:9], v[142:143] op_sel_hi:[1,0]
	v_pk_mul_f32 v[6:7], v[6:7], v[142:143] op_sel_hi:[1,0]
	v_pk_mul_f32 v[4:5], v[4:5], v[142:143] op_sel_hi:[1,0]
	v_pk_mul_f32 v[2:3], v[2:3], v[142:143] op_sel_hi:[1,0]
	v_pk_mul_f32 v[0:1], v[0:1], v[142:143] op_sel_hi:[1,0]
	s_branch .LBB0_964
